# grid barrier arrivals sharded over 4 counter words in separate 256-B lines (by block id & 3), pollers sum the 4 words; words zeroed by block 0 at kernel start like the original counter
# speedup vs baseline: 1.0286x; 1.0189x over previous
; __global__ __launch_bounds__(NTHR, 1) void hymba_mega(Params P) {
;   extern __shared__ __attribute__((aligned(16))) char lds[];
;   cg::grid_group grid = cg::this_grid();
;   unsigned* bctr = reinterpret_cast<unsigned*>(P.ws + O_CONST + 8192 - 256);
;   if (blockIdx.x == 0 && threadIdx.x == 0) *bctr = 0u;
;   if (blockIdx.x == 0 && threadIdx.x < 64) reinterpret_cast<unsigned*>(P.ws + O_CONST + 8192 - 512)[threadIdx.x] = 0u;
_Z10hymba_mega6Params:
	s_load_dwordx8 s[52:59], s[0:1], 0x80
	s_load_dword s26, s[0:1], 0xa0
	s_mov_b32 s98, s2
	v_and_b32_e32 v226, 0x3ff, v0
	s_add_u32 s2, s0, 0xa0
	v_or_b32_e32 v1, s98, v226
	s_addc_u32 s3, s1, 0
	v_cmp_eq_u32_e32 vcc, 0, v1
	s_and_saveexec_b64 s[4:5], vcc
	s_cbranch_execz .LBB0_2
	v_mov_b32_e32 v1, 0xf7a1000
	v_mov_b32_e32 v2, 0
	s_waitcnt lgkmcnt(0)
	global_store_dword v1, v2, s[58:59] offset:3840
	global_store_dword v1, v2, s[58:59] offset:-1024
	global_store_dword v1, v2, s[58:59] offset:-768
	global_store_dword v1, v2, s[58:59] offset:-512
	global_store_dword v1, v2, s[58:59] offset:-256

; DEV void grid_bar(unsigned* ctr, unsigned target) {
;   asm volatile("s_waitcnt vmcnt(0)" ::: "memory");
;   __syncthreads();
;   if (threadIdx.x == 0) {
;     __builtin_amdgcn_fence(__ATOMIC_RELEASE, "agent");
;     asm volatile("s_waitcnt vmcnt(0)" ::: "memory");
;     __hip_atomic_fetch_add(ctr, 1u, __ATOMIC_RELAXED, __HIP_MEMORY_SCOPE_AGENT);
;     while (__hip_atomic_load(ctr, __ATOMIC_RELAXED, __HIP_MEMORY_SCOPE_AGENT) < target) __builtin_amdgcn_s_sleep(1);
;     __builtin_amdgcn_fence(__ATOMIC_ACQUIRE, "agent");
;     asm volatile("s_waitcnt vmcnt(0)" ::: "memory");
;   }
;   __syncthreads();
; }
.LBB0_348:
	s_waitcnt vmcnt(0)
	s_waitcnt vmcnt(0) lgkmcnt(0)
	s_barrier
	s_and_saveexec_b64 s[2:3], s[0:1]
	s_cbranch_execz .LBB0_353
	v_mov_b32_e32 v0, s86
	v_add_co_u32_e32 v0, vcc, 0xf7a1000, v0
	v_mov_b32_e32 v1, s87
	buffer_wbl2 sc1
	s_waitcnt vmcnt(0)
	v_addc_co_u32_e32 v1, vcc, 0, v1, vcc
	v_readlane_b32 s12, v254, 26
	v_readlane_b32 s4, v254, 40
	s_add_i32 s10, s4, 1
	s_add_u32 s4, s86, 0xf7a1f00
	s_mul_i32 s10, s10, s94
	s_addc_u32 s5, s87, 0
	s_and_b32 s12, s12, 3
	s_lshl_b32 s12, s12, 8
	s_sub_u32 s4, s4, 0x1300
	s_subb_u32 s5, s5, 0
	s_add_u32 s12, s4, s12
	s_addc_u32 s13, s5, 0
	v_mov_b32_e32 v0, s12
	v_mov_b32_e32 v1, s13
	flat_atomic_add v[0:1], v228
	s_mov_b32 s11, 0
.Lgb_loop_0:
	v_mov_b64_e32 v[0:1], s[4:5]
	flat_load_dword v240, v[0:1] sc1
	flat_load_dword v241, v[0:1] offset:256 sc1
	flat_load_dword v242, v[0:1] offset:512 sc1
	flat_load_dword v243, v[0:1] offset:768 sc1
	s_waitcnt vmcnt(0) lgkmcnt(0)
	v_add_u32_e32 v240, v240, v241
	v_add3_u32 v240, v240, v242, v243
	s_nop 0
	v_readfirstlane_b32 s12, v240
	s_cmp_ge_u32 s12, s10
	s_cbranch_scc1 .Lgb_done_0
	s_sleep 6
	s_add_u32 s11, s11, 1
	s_cmp_lt_u32 s11, 0x20000
	s_cbranch_scc1 .Lgb_loop_0
.Lgb_done_0:
	buffer_inv sc1
	s_waitcnt vmcnt(0)

; DEV void grid_bar(unsigned* ctr, unsigned target) {
;   asm volatile("s_waitcnt vmcnt(0)" ::: "memory");
;   __syncthreads();
;   if (threadIdx.x == 0) {
;     __builtin_amdgcn_fence(__ATOMIC_RELEASE, "agent");
;     asm volatile("s_waitcnt vmcnt(0)" ::: "memory");
;     __hip_atomic_fetch_add(ctr, 1u, __ATOMIC_RELAXED, __HIP_MEMORY_SCOPE_AGENT);
;     while (__hip_atomic_load(ctr, __ATOMIC_RELAXED, __HIP_MEMORY_SCOPE_AGENT) < target) __builtin_amdgcn_s_sleep(1);
;     __builtin_amdgcn_fence(__ATOMIC_ACQUIRE, "agent");
;     asm volatile("s_waitcnt vmcnt(0)" ::: "memory");
;   }
;   __syncthreads();
; }
.LBB0_360:
	s_waitcnt vmcnt(0)
	s_barrier
	s_and_saveexec_b64 s[2:3], s[0:1]
	s_cbranch_execz .LBB0_365
	v_mov_b32_e32 v0, s4
	v_add_co_u32_e32 v0, vcc, 0xf7a1000, v0
	v_mov_b32_e32 v1, s5
	buffer_wbl2 sc1
	s_waitcnt vmcnt(0)
	s_waitcnt vmcnt(0)
	v_addc_co_u32_e32 v1, vcc, 0, v1, vcc
	v_readlane_b32 s12, v254, 26
	v_readlane_b32 s6, v254, 40
	s_add_i32 s10, s6, 2
	s_add_u32 s4, s4, 0xf7a1f00
	s_mul_i32 s10, s10, s94
	s_addc_u32 s5, s5, 0
	s_and_b32 s12, s12, 3
	s_lshl_b32 s12, s12, 8
	s_sub_u32 s4, s4, 0x1300
	s_subb_u32 s5, s5, 0
	s_add_u32 s12, s4, s12
	s_addc_u32 s13, s5, 0
	v_mov_b32_e32 v0, s12
	v_mov_b32_e32 v1, s13
	flat_atomic_add v[0:1], v228
	s_mov_b32 s11, 0

; DEV void grid_bar(unsigned* ctr, unsigned target) {
;   asm volatile("s_waitcnt vmcnt(0)" ::: "memory");
;   __syncthreads();
;   if (threadIdx.x == 0) {
;     __builtin_amdgcn_fence(__ATOMIC_RELEASE, "agent");
;     asm volatile("s_waitcnt vmcnt(0)" ::: "memory");
;     __hip_atomic_fetch_add(ctr, 1u, __ATOMIC_RELAXED, __HIP_MEMORY_SCOPE_AGENT);
;     while (__hip_atomic_load(ctr, __ATOMIC_RELAXED, __HIP_MEMORY_SCOPE_AGENT) < target) __builtin_amdgcn_s_sleep(1);
;     __builtin_amdgcn_fence(__ATOMIC_ACQUIRE, "agent");
;     asm volatile("s_waitcnt vmcnt(0)" ::: "memory");
;   }
;   __syncthreads();
; }
.LBB0_399:
	s_waitcnt vmcnt(0)
	v_readlane_b32 s2, v254, 40
	s_add_i32 s34, s2, 3
	s_barrier
	s_and_saveexec_b64 s[2:3], s[0:1]
	s_cbranch_execz .LBB0_404
	v_mov_b32_e32 v0, s4
	v_add_co_u32_e32 v0, vcc, 0xf7a1000, v0
	v_mov_b32_e32 v1, s5
	buffer_wbl2 sc1
	s_waitcnt vmcnt(0)
	s_waitcnt vmcnt(0)
	v_addc_co_u32_e32 v1, vcc, 0, v1, vcc
	v_readlane_b32 s12, v254, 26
	s_add_u32 s4, s4, 0xf7a1f00
	s_mul_i32 s10, s34, s94
	s_addc_u32 s5, s5, 0
	s_and_b32 s12, s12, 3
	s_lshl_b32 s12, s12, 8
	s_sub_u32 s4, s4, 0x1300
	s_subb_u32 s5, s5, 0
	s_add_u32 s12, s4, s12
	s_addc_u32 s13, s5, 0
	v_mov_b32_e32 v0, s12
	v_mov_b32_e32 v1, s13
	flat_atomic_add v[0:1], v228
	s_mov_b32 s11, 0

; DEV void grid_bar(unsigned* ctr, unsigned target) {
;   asm volatile("s_waitcnt vmcnt(0)" ::: "memory");
;   __syncthreads();
;   if (threadIdx.x == 0) {
;     __builtin_amdgcn_fence(__ATOMIC_RELEASE, "agent");
;     asm volatile("s_waitcnt vmcnt(0)" ::: "memory");
;     __hip_atomic_fetch_add(ctr, 1u, __ATOMIC_RELAXED, __HIP_MEMORY_SCOPE_AGENT);
;     while (__hip_atomic_load(ctr, __ATOMIC_RELAXED, __HIP_MEMORY_SCOPE_AGENT) < target) __builtin_amdgcn_s_sleep(1);
;     __builtin_amdgcn_fence(__ATOMIC_ACQUIRE, "agent");
;     asm volatile("s_waitcnt vmcnt(0)" ::: "memory");
;   }
;   __syncthreads();
; }
.LBB0_474:
	v_readlane_b32 s2, v254, 41
	v_readlane_b32 s3, v254, 42
	s_and_b64 s[2:3], s[96:97], s[2:3]
	s_and_b64 vcc, exec, s[2:3]
	s_cbranch_vccnz .LBB0_481
	s_waitcnt vmcnt(0)
	v_readlane_b32 s2, v254, 40
	s_add_i32 s34, s2, 4
	s_waitcnt lgkmcnt(0)
	s_barrier
	s_and_saveexec_b64 s[2:3], s[0:1]
	s_cbranch_execz .LBB0_480
	v_mov_b32_e32 v0, s10
	v_add_co_u32_e32 v0, vcc, 0xf7a1000, v0
	v_mov_b32_e32 v1, s11
	buffer_wbl2 sc1
	s_waitcnt vmcnt(0)
	s_waitcnt vmcnt(0)
	v_addc_co_u32_e32 v1, vcc, 0, v1, vcc
	v_readlane_b32 s12, v254, 26
	s_add_u32 s4, s10, 0xf7a1f00
	s_mul_i32 s10, s34, s94
	s_addc_u32 s5, s11, 0
	s_and_b32 s12, s12, 3
	s_lshl_b32 s12, s12, 8
	s_sub_u32 s4, s4, 0x1300
	s_subb_u32 s5, s5, 0
	s_add_u32 s12, s4, s12
	s_addc_u32 s13, s5, 0
	v_mov_b32_e32 v0, s12
	v_mov_b32_e32 v1, s13
	flat_atomic_add v[0:1], v228
	s_mov_b32 s11, 0
